# NA window task: the head's bias table copied to LDS with all eight loads of a lane in flight (the copy loop waited for each load)
# speedup vs baseline: 1.0056x; 1.0056x over previous
; __device__ __forceinline__ void na_task(const P& p, int task, int lane, float* ldsw  ) {
;     const int fr = lane & 15, g = lane >> 4;
;     const bf16_t* QK = (const bf16_t*)(p.ws + WS_NAQK); const bf16_t* VT = (const bf16_t*)(p.ws + WS_NAVT); bf16_t* Y = (bf16_t*)(p.ws + WS_A);
;     if (task < 2048) {
;         const int h = task & 7, r = (task >> 3) & 31, b = task >> 8;
;         for (int i = lane; i < 465; i += 64) ldsw[i] = p.rpb[h * 465 + i];
;         AttnState st[4];
;         bf16_t* qlds = (bf16_t*)(ldsw + 512) + fr * 72 + g * 8;
;         const size_t qrow0 = (size_t)b * TLAT + r * 64 + fr;
; #pragma unroll
;         for (int j = 0; j < 4; ++j) {
;             st[j].m = -1e30f; st[j].l = 0.f;
; #pragma unroll
;             for (int dt = 0; dt < 4; ++dt) st[j].o[dt] = (f32x4){0.f, 0.f, 0.f, 0.f};
;             const bf16_t* qp = QK + (qrow0 + j * 16) * 1024 + h * 64 + g * 8;
;             *(bf16x8*)(qlds + j * 16 * 72) = *(const bf16x8*)qp; *(bf16x8*)(qlds + j * 16 * 72 + 32) = *(const bf16x8*)(qp + 32);
;         }
;         const int r0 = clampi(r - 4, 0, 24);
;         const bf16_t* vb = VT + ((size_t)b * 512 + h * 64) * TT;
;         const bf16_t* kbase = QK + 512 + h * 64 + g * 8;
;         auto ldk = [&](int i, AttnKn& k) {
;             const bf16_t* k0p = (i < 16) ? kbase + ((size_t)b * TLAT + (r0 + (i >> 1)) * 64 + (i & 1) * 32 + fr) * 1024 : kbase + ((size_t)MLAT + b * TCTX + (i - 16) * 32 + fr) * 1024;
;             k.a00 = *(const bf16x8*)k0p; k.a01 = *(const bf16x8*)(k0p + 32); k.a10 = *(const bf16x8*)(k0p + 16 * 1024); k.a11 = *(const bf16x8*)(k0p + 16 * 1024 + 32);
;         };
;         auto ldv = [&](int i, AttnVn& v) {
;             const int tok0 = (i < 16) ? (r0 + (i >> 1)) * 64 + (i & 1) * 32 : TLAT + (i - 16) * 32;
; #pragma unroll
;             for (int dt = 0; dt < 4; ++dt) { const bf16_t* vp = vb + (size_t)(dt * 16 + fr) * TT + tok0 + 4 * g; v.va[dt][0] = *(const s16x4*)vp; v.va[dt][1] = *(const s16x4*)(vp + 16); }
;         };
;         asm volatile("s_waitcnt lgkmcnt(0)" ::: "memory");
;         AttnKn kc, kn; AttnVn vv; ldk(0, kc);
; #pragma unroll 1
;         for (int i = 0; i < 24; ++i) {
;             ldk(i + 1 < 24 ? i + 1 : i, kn);
;             ldv(i, vv);
;             const int half = i & 1;
;             const float* rp = ldsw + (r0 + (i >> 1) - r + 7) * 31;
; #pragma unroll
.LBB0_378:
	s_or_b64 exec, exec, s[2:3]
	v_mov_b32_e32 v0, v1
	s_waitcnt lgkmcnt(0)
	s_barrier
	v_readlane_b32 s2, v254, 18
	v_readfirstlane_b32 s49, v144
	s_ashr_i32 s48, s49, 6
	s_add_i32 s84, s2, s48
	s_cmpk_gt_i32 s84, 0xbff
	v_readfirstlane_b32 s2, v0
	s_cbranch_scc1 .LBB0_418
	s_load_dwordx2 s[44:45], s[92:93], s2 offset:0x58
	s_load_dwordx2 s[46:47], s[92:93], s2 offset:0xa8
	s_mul_i32 s2, s48, 0x3000
	v_and_b32_e32 v2, 48, v144
	v_mov_b32_e32 v3, v1
	s_add_i32 s85, s2, 0
	v_and_b32_e32 v114, 15, v144
	s_waitcnt lgkmcnt(0)
	v_lshl_add_u64 v[4:5], s[46:47], 0, v[2:3]
	s_mov_b64 s[6:7], 0x7f00400
	s_add_u32 s2, s46, 0x7f00000
	v_lshl_add_u64 v[116:117], v[4:5], 0, s[6:7]
	v_mul_u32_u24_e32 v4, 0x90, v114
	v_bfe_u32 v6, v144, 4, 2
	s_addc_u32 s3, s47, 0
	v_add3_u32 v143, s85, v4, v2
	v_subrev_co_u32_e32 v4, vcc, 8, v114
	s_add_u32 s86, s46, 0xa300000
	v_min_u32_e32 v4, 48, v4
	v_lshlrev_b32_e32 v124, 2, v6
	s_addc_u32 s87, s47, 0
	v_cndmask_b32_e64 v8, v4, 0, vcc
	v_or_b32_e32 v170, 16, v124
	s_add_u32 s76, s46, 0x5b00000
	v_add_u32_e32 v9, 16, v8
	v_cmp_lt_u32_e64 s[8:9], v124, v8
	v_cmp_ge_u32_e32 vcc, v170, v8
	v_or_b32_e32 v172, 17, v124
	s_addc_u32 s77, s47, 0
	s_and_b64 s[14:15], vcc, s[8:9]
	v_cmp_ge_u32_e32 vcc, v172, v8
	v_cmp_lt_u32_e64 s[16:17], v172, v9
	v_or_b32_e32 v174, 18, v124
	v_and_b32_e32 v7, 63, v144
	v_or_b32_e32 v167, 1, v124
	v_or_b32_e32 v168, 3, v124
	v_or_b32_e32 v169, 2, v124
	v_sub_u32_e32 v10, v170, v114
	s_and_b64 s[16:17], vcc, s[16:17]
	v_cmp_ge_u32_e32 vcc, v174, v8
	v_cmp_lt_u32_e64 s[18:19], v174, v9
	v_or_b32_e32 v176, 19, v124
	v_or_b32_e32 v5, 48, v7
	v_cmp_lt_u32_e64 s[6:7], v167, v8
	v_cmp_lt_u32_e64 s[10:11], v168, v8
	v_cmp_lt_u32_e64 s[12:13], v169, v8
	v_min_u32_e32 v171, 15, v10
	v_sub_u32_e32 v10, v172, v114
	s_and_b64 s[18:19], vcc, s[18:19]
	v_cmp_ge_u32_e32 vcc, v176, v8
	v_sub_u32_e32 v8, v176, v114
	v_min_u32_e32 v173, 15, v10
	v_sub_u32_e32 v10, v174, v114
	v_min_u32_e32 v177, 15, v8
	v_add_u32_e32 v8, -8, v5
	v_min_u32_e32 v175, 15, v10
	v_min_u32_e32 v8, 48, v8
	v_or_b32_e32 v10, 32, v124
	v_cmp_lt_u32_e64 s[22:23], v10, v8
	v_sub_u32_e32 v10, v10, v5
	v_sub_u32_e64 v183, v10, -15 clamp
	v_or_b32_e32 v10, 33, v124
	v_cmp_lt_u32_e64 s[24:25], v10, v8
	v_sub_u32_e32 v10, v10, v5
	v_sub_u32_e64 v207, v10, -15 clamp
	v_or_b32_e32 v10, 34, v124
	v_cmp_lt_u32_e64 s[26:27], v10, v8
	v_sub_u32_e32 v10, v10, v5
	s_bfe_u32 s49, s49, 0x30006
	v_sub_u32_e64 v208, v10, -15 clamp
	v_or_b32_e32 v10, 35, v124
	v_lshl_add_u64 v[2:3], s[2:3], 0, v[2:3]
	s_lshl_b32 s64, s49, 7
	v_cmp_lt_u32_e64 s[20:21], v176, v9
	v_add_u32_e32 v9, 16, v8
	v_cmp_lt_u32_e64 s[28:29], v10, v8
	v_sub_u32_e32 v8, v10, v5
	v_lshl_add_u64 v[126:127], v[2:3], 0, s[64:65]
	v_lshrrev_b32_e32 v2, 1, v144
	v_sub_u32_e64 v209, v8, -15 clamp
	v_or_b32_e32 v8, 49, v124
	v_or_b32_e32 v10, 48, v124
	v_and_b32_e32 v2, 24, v2
	v_mov_b32_e32 v3, v1
	v_lshlrev_b32_e32 v0, 3, v6
	v_sub_u32_e32 v210, v10, v5
	v_cmp_lt_u32_e64 s[30:31], v8, v9
	v_cmp_lt_u32_e64 s[34:35], v10, v9
	v_or_b32_e32 v8, 51, v124
	v_or_b32_e32 v10, 50, v124
	s_mul_i32 s50, s49, 0x1d1
	v_lshl_add_u64 v[132:133], s[46:47], 0, v[2:3]
	v_readlane_b32 s46, v254, 19
	v_mul_u32_u24_e32 v118, 0x1200, v114
	v_or_b32_e32 v4, 0x800, v124
	v_or_b32_e32 v6, 0x810, v124
	v_cmp_lt_u32_e64 s[40:41], v8, v9
	v_cmp_lt_u32_e64 s[42:43], v10, v9
	v_lshl_add_u64 v[8:9], s[76:77], 0, v[0:1]
	s_add_i32 s89, s46, s48
	s_lshl_b32 s46, s48, 6
	v_readlane_b32 s47, v254, 21
	v_add_lshl_u32 v2, s50, v7, 2
	v_mov_b32_e32 v119, v1
	v_mul_u32_u24_e32 v120, 0x1200, v5
	v_mov_b32_e32 v121, v1
	v_or_b32_e32 v125, 0x4000, v114
	v_mov_b32_e32 v115, v1
	v_mul_hi_u32_u24_e32 v123, 0x1200, v114
	v_mov_b32_e32 v122, v118
	v_bitop3_b32 v145, v144, 15, v144 bitop3:0xc
	s_and_b64 s[20:21], vcc, s[20:21]
	v_or_b32_e32 v178, 16, v114
	v_add_u32_e32 v179, 8, v114
	v_add_u32_e32 v180, 24, v114
	v_or_b32_e32 v181, 32, v114
	v_add_u32_e32 v182, 40, v114
	v_sub_u32_e32 v211, v10, v5
	s_lshl_b32 s88, s49, 6
	v_lshl_add_u64 v[128:129], v[116:117], 0, s[64:65]
	v_lshl_add_u64 v[130:131], v[8:9], 0, s[64:65]
	s_add_i32 s90, s47, s46
	v_lshl_add_u32 v212, v7, 2, s85
	v_or_b32_e32 v213, 0xffffffc0, v7
	v_lshl_add_u64 v[134:135], s[44:45], 0, v[2:3]
	v_lshlrev_b32_e32 v136, 1, v0
	v_lshlrev_b32_e32 v146, 1, v4
	v_lshlrev_b32_e32 v148, 1, v6
	s_branch .LBB0_382
	s_nop 0
	s_nop 0
	s_nop 0
	s_nop 0
	s_nop 0
	s_nop 0
	s_nop 0
	s_nop 0
	s_nop 0
	s_nop 0
	s_nop 0
	s_nop 0

; __device__ __forceinline__ void na_task(const P& p, int task, int lane, float* ldsw  ) {
;     ...
;         for (int i = lane; i < 465; i += 64) ldsw[i] = p.rpb[h * 465 + i];
;         AttnState st[4];
;         bf16_t* qlds = (bf16_t*)(ldsw + 512) + fr * 72 + g * 8;
;         const size_t qrow0 = (size_t)b * TLAT + r * 64 + fr;
; #pragma unroll
;         for (int j = 0; j < 4; ++j) {
;             st[j].m = -1e30f; st[j].l = 0.f;
; #pragma unroll
;             for (int dt = 0; dt < 4; ++dt) st[j].o[dt] = (f32x4){0.f, 0.f, 0.f, 0.f};
;             const bf16_t* qp = QK + (qrow0 + j * 16) * 1024 + h * 64 + g * 8;
;             *(bf16x8*)(qlds + j * 16 * 72) = *(const bf16x8*)qp; *(bf16x8*)(qlds + j * 16 * 72 + 32) = *(const bf16x8*)(qp + 32);
;         }
;         const int r0 = clampi(r - 4, 0, 24);
;         const bf16_t* vb = VT + ((size_t)b * 512 + h * 64) * TT;
;         const bf16_t* kbase = QK + 512 + h * 64 + g * 8;
;         auto ldk = [&](int i, AttnKn& k) {
;             const bf16_t* k0p = (i < 16) ? kbase + ((size_t)b * TLAT + (r0 + (i >> 1)) * 64 + (i & 1) * 32 + fr) * 1024 : kbase + ((size_t)MLAT + b * TCTX + (i - 16) * 32 + fr) * 1024;
;             k.a00 = *(const bf16x8*)k0p; k.a01 = *(const bf16x8*)(k0p + 32); k.a10 = *(const bf16x8*)(k0p + 16 * 1024); k.a11 = *(const bf16x8*)(k0p + 16 * 1024 + 32);
;         };
;         auto ldv = [&](int i, AttnVn& v) {
;             const int tok0 = (i < 16) ? (r0 + (i >> 1)) * 64 + (i & 1) * 32 : TLAT + (i - 16) * 32;
; #pragma unroll
;             for (int dt = 0; dt < 4; ++dt) { const bf16_t* vp = vb + (size_t)(dt * 16 + fr) * TT + tok0 + 4 * g; v.va[dt][0] = *(const s16x4*)vp; v.va[dt][1] = *(const s16x4*)(vp + 16); }
;         };
;         asm volatile("s_waitcnt lgkmcnt(0)" ::: "memory");
;         AttnKn kc, kn; AttnVn vv; ldk(0, kc);
.LBB0_388:
	v_cmp_gt_i32_e32 vcc, 0xffffffd1, v213
	global_load_dword v5, v[2:3], off
	global_load_dword v6, v[2:3], off offset:256
	global_load_dword v7, v[2:3], off offset:512
	global_load_dword v8, v[2:3], off offset:768
	global_load_dword v9, v[2:3], off offset:1024
	global_load_dword v10, v[2:3], off offset:1280
	global_load_dword v11, v[2:3], off offset:1536
	s_and_saveexec_b64 s[46:47], vcc
	global_load_dword v12, v[2:3], off offset:1792
	s_waitcnt vmcnt(0)
	ds_write_b32 v4, v12 offset:1792
	s_or_b64 exec, exec, s[46:47]
	ds_write_b32 v4, v5
	ds_write_b32 v4, v6 offset:256
	ds_write_b32 v4, v7 offset:512
	ds_write_b32 v4, v8 offset:768
	ds_write_b32 v4, v9 offset:1024
	ds_write_b32 v4, v10 offset:1280
	ds_write_b32 v4, v11 offset:1536
	s_or_b64 exec, exec, s[44:45]
	s_ashr_i32 s44, s84, 8
	s_bfe_u32 s49, s84, 0x50003
	s_ashr_i32 s45, s44, 31
	s_lshl_b64 s[80:81], s[44:45], 11
	v_lshl_or_b32 v0, s49, 6, v114
	v_or_b32_e32 v34, s80, v0
	v_mov_b32_e32 v35, s81
	v_lshlrev_b64 v[156:157], 11, v[34:35]
	v_or_b32_e32 v154, 0x8000, v156
	v_mov_b32_e32 v155, v157
	v_or_b32_e32 v152, 0x10000, v156
	v_mov_b32_e32 v153, v157
	v_or_b32_e32 v150, 0x18000, v156
	v_mov_b32_e32 v151, v157
	v_lshl_add_u64 v[6:7], v[126:127], 0, v[156:157]
	v_lshl_add_u64 v[14:15], v[126:127], 0, v[154:155]
	v_lshl_add_u64 v[22:23], v[126:127], 0, v[152:153]
	v_lshl_add_u64 v[30:31], v[126:127], 0, v[150:151]
	global_load_dwordx4 v[2:5], v[6:7], off
	s_nop 0
	global_load_dwordx4 v[6:9], v[6:7], off offset:64
	s_nop 0
	global_load_dwordx4 v[10:13], v[14:15], off
	s_nop 0
	global_load_dwordx4 v[14:17], v[14:15], off offset:64
	s_nop 0
	global_load_dwordx4 v[18:21], v[22:23], off
	s_nop 0
	global_load_dwordx4 v[22:25], v[22:23], off offset:64
	s_nop 0
	global_load_dwordx4 v[26:29], v[30:31], off
	s_nop 0
	global_load_dwordx4 v[30:33], v[30:31], off offset:64
	v_sub_co_u32_e64 v0, s[46:47], s49, 4
	v_min_u32_e32 v0, 24, v0
	s_nop 0
	v_cndmask_b32_e64 v147, v0, 0, s[46:47]
	v_lshlrev_b32_e32 v0, 6, v147
	v_or_b32_e32 v0, s80, v0
	v_or_b32_e32 v34, v0, v114
	v_lshlrev_b64 v[34:35], 11, v[34:35]
	v_lshl_add_u64 v[34:35], v[128:129], 0, v[34:35]
	v_add_co_u32_e32 v36, vcc, s60, v34
	s_lshl_b32 s44, s44, 9
	s_nop 0
	v_addc_co_u32_e32 v37, vcc, 0, v35, vcc
	s_or_b32 s44, s44, s88
	s_mulk_i32 s45, 0x1200
	s_mul_hi_u32 s46, s44, 0x1200
	s_add_i32 s46, s46, s45
	s_mulk_i32 s44, 0x1200
	s_add_u32 s44, s86, s44
	s_addc_u32 s45, s87, s46
	v_lshlrev_b32_e32 v0, 1, v124
	s_mov_b64 s[46:47], 0x12000
	s_and_b32 s50, s84, 0xffffff00
	v_mov_b32_e32 v216, 0
	s_mov_b32 s48, 0
	v_subrev_u32_e32 v149, s49, v147
	s_ashr_i32 s52, s50, 31
	v_mov_b32_e32 v166, 0xf149f2ca
	s_movk_i32 s62, 0x600
	v_mov_b32_e32 v214, 0
	v_mov_b32_e32 v221, 0xf149f2ca
	v_mov_b32_e32 v215, 0
	v_mov_b32_e32 v218, 0xf149f2ca
	v_mov_b32_e32 v217, 0xf149f2ca
	v_mov_b32_e32 v137, 0
	v_mov_b32_e32 v38, 0
	v_mov_b32_e32 v39, v216
	v_mov_b32_e32 v40, v216
	v_mov_b32_e32 v41, v216
	v_mov_b32_e32 v42, 0
	v_mov_b32_e32 v43, v216
	v_mov_b32_e32 v44, v216
	v_mov_b32_e32 v45, v216
	v_mov_b32_e32 v50, 0
	v_mov_b32_e32 v51, v216
	v_mov_b32_e32 v52, v216
	v_mov_b32_e32 v53, v216
	s_waitcnt vmcnt(7)
	ds_write_b128 v143, v[2:5] offset:2048
	s_waitcnt vmcnt(6)
	ds_write_b128 v143, v[6:9] offset:2112
	s_waitcnt vmcnt(5)
	ds_write_b128 v143, v[10:13] offset:4352
	s_waitcnt vmcnt(4)
	ds_write_b128 v143, v[14:17] offset:4416
	s_waitcnt vmcnt(3)
	ds_write_b128 v143, v[18:21] offset:6656
	s_waitcnt vmcnt(2)
	ds_write_b128 v143, v[22:25] offset:6720
	s_waitcnt vmcnt(1)
	ds_write_b128 v143, v[26:29] offset:8960
	s_waitcnt vmcnt(0)
	ds_write_b128 v143, v[30:33] offset:9024
	s_waitcnt lgkmcnt(0)
	global_load_dwordx4 v[78:81], v[34:35], off
	global_load_dwordx4 v[70:73], v[34:35], off offset:64
	global_load_dwordx4 v[74:77], v[36:37], off
	global_load_dwordx4 v[66:69], v[36:37], off offset:64
	v_lshl_add_u64 v[2:3], s[44:45], 0, v[122:123]
	v_lshl_add_u64 v[158:159], v[2:3], 0, v[0:1]
	v_lshl_add_u64 v[2:3], s[44:45], 0, v[118:119]
	v_lshl_add_u64 v[2:3], v[2:3], 0, v[0:1]
	v_lshl_add_u64 v[160:161], v[2:3], 0, s[46:47]
	s_mov_b64 s[46:47], 0x24000
	v_lshl_add_u64 v[162:163], v[2:3], 0, s[46:47]
	v_lshl_add_u64 v[2:3], s[44:45], 0, v[120:121]
	v_lshl_add_u64 v[164:165], v[2:3], 0, v[0:1]
	v_mov_b32_e32 v2, v1
	v_mov_b32_e32 v3, v1
	v_mov_b32_e32 v0, v1
	v_mov_b64_e32 v[48:49], v[2:3]
	v_mov_b64_e32 v[56:57], v[2:3]
	v_mov_b64_e32 v[60:61], v[2:3]
	v_mov_b64_e32 v[64:65], v[2:3]
	v_mov_b64_e32 v[16:17], v[2:3]
	v_mov_b64_e32 v[12:13], v[2:3]
	v_mov_b64_e32 v[8:9], v[2:3]
	v_mov_b64_e32 v[46:47], v[0:1]
	v_mov_b64_e32 v[54:55], v[0:1]
	v_mov_b64_e32 v[58:59], v[0:1]
	v_mov_b64_e32 v[62:63], v[0:1]
	v_mov_b64_e32 v[14:15], v[0:1]
	v_mov_b64_e32 v[10:11], v[0:1]
	v_mov_b64_e32 v[6:7], v[0:1]
	v_mov_b64_e32 v[4:5], v[2:3]
	v_mov_b64_e32 v[2:3], v[0:1]
	v_mov_b32_e32 v34, 0
	v_mov_b32_e32 v35, v216
	v_mov_b32_e32 v36, v216
	v_mov_b32_e32 v37, v216
	v_mov_b32_e32 v30, 0
	v_mov_b32_e32 v31, v216
	v_mov_b32_e32 v32, v216
	v_mov_b32_e32 v33, v216
	v_mov_b32_e32 v26, 0
	v_mov_b32_e32 v27, v216
	v_mov_b32_e32 v28, v216
	v_mov_b32_e32 v29, v216
	v_mov_b32_e32 v22, 0
	v_mov_b32_e32 v23, v216
	v_mov_b32_e32 v24, v216
	v_mov_b32_e32 v25, v216
	v_mov_b32_e32 v18, 0
	v_mov_b32_e32 v19, v216
	v_mov_b32_e32 v20, v216
	v_mov_b32_e32 v21, v216
